# LayerNorm reductions: xor-32/16 steps via v_permlane32_swap / v_permlane16_swap (no LDS crossbar left in the LN loop)
# speedup vs baseline: 1.0121x; 1.0043x over previous
; DI void phase_ln(const P& p, int l) {
;     ...
;     for (int h = 0; h < 2; ++h) {
;       if (h && !two) break;
;       const int rr = h ? rowb : row;
;       float s = 0.f;
; #pragma unroll
;       for (int i = 0; i < 4; ++i) s += (v[h][i].x + v[h][i].y) + (v[h][i].z + v[h][i].w);
; #pragma unroll
;       for (int o = 32; o >= 1; o >>= 1) s += __shfl_xor(s, o);
;       const float mean = s * (1.f / 1024.f);
;       float q = 0.f;
; #pragma unroll
;       for (int i = 0; i < 4; ++i) {
;         v[h][i].x -= mean; v[h][i].y -= mean; v[h][i].z -= mean; v[h][i].w -= mean;
;         q += (v[h][i].x * v[h][i].x + v[h][i].y * v[h][i].y) + (v[h][i].z * v[h][i].z + v[h][i].w * v[h][i].w);
;       }
; #pragma unroll
;       for (int o = 32; o >= 1; o >>= 1) q += __shfl_xor(q, o);
;       const float rstd = rsqrtf(q * (1.f / 1024.f) + 1e-5f);
;       const int mr = rr < MLAT ? (rr >> 11) : 16;
;       const float* md = p.mod + (size_t)(1 * 17 + mr) * 3072;
; #pragma unroll
;       for (int i = 0; i < 4; ++i) {
;         const int col = i * 256 + lane * 4;
;         float4 y;
;         y.x = v[h][i].x * rstd * g4[i].x + b4[i].x;
;         y.y = v[h][i].y * rstd * g4[i].y + b4[i].y;
;         y.z = v[h][i].z * rstd * g4[i].z + b4[i].z;
;         y.w = v[h][i].w * rstd * g4[i].w + b4[i].w;
;         if (l == 1 || rr < MLAT) *(float4*)(p.out + (size_t)rr * 1024 + col) = y;
.Lln_nopf:
	v_add_u32_e32 v63, 1, v62
	v_cmp_lt_i32_e64 s[40:41], v63, v65
	v_lshl_add_u64 v[90:91], v[80:81], 0, v[78:79]
	v_cmp_gt_i32_e32 vcc, s21, v62
	v_cndmask_b32_e64 v86, v62, v63, s[40:41]
	v_ashrrev_i32_e32 v87, 31, v86
	v_lshlrev_b64 v[88:89], 12, v[86:87]
	v_lshl_add_u64 v[38:39], v[66:67], 0, v[88:89]
	global_load_dwordx4 v[34:37], v[38:39], off
	global_load_dwordx4 v[46:49], v[38:39], off offset:1024
	global_load_dwordx4 v[42:45], v[38:39], off offset:2048
	s_nop 0
	global_load_dwordx4 v[38:41], v[38:39], off offset:3072
	s_nop 0
	global_load_dwordx4 v[50:53], v[90:91], off offset:3072
	global_load_dwordx4 v[54:57], v[90:91], off offset:2048
	global_load_dwordx4 v[58:61], v[90:91], off offset:1024
	s_or_b64 s[52:53], s[46:47], vcc
	s_waitcnt vmcnt(1)
	v_mov_b32_e32 v0, v57
	s_waitcnt vmcnt(0)
	v_mov_b32_e32 v92, v58
	v_mov_b32_e32 v93, v60
	v_mov_b32_e32 v98, v59
	v_mov_b32_e32 v99, v61
	v_pk_add_f32 v[92:93], v[92:93], v[98:99]
	v_pk_add_f32 v[94:95], v[56:57], v[0:1]
	v_pk_add_f32 v[98:99], v[92:93], v[92:93] op_sel:[0,1] op_sel_hi:[1,0]
	global_load_dwordx4 v[90:93], v[90:91], off
	v_mov_b32_e32 v0, v55
	v_pk_add_f32 v[96:97], v[54:55], v[0:1]
	v_mov_b32_e32 v95, v53
	v_mov_b32_e32 v97, v52
	v_mov_b32_e32 v99, v51
	v_pk_add_f32 v[94:95], v[96:97], v[94:95]
	s_waitcnt vmcnt(0)
	v_mov_b32_e32 v100, v90
	v_mov_b32_e32 v101, v92
	v_mov_b32_e32 v106, v91
	v_mov_b32_e32 v107, v93
	v_pk_add_f32 v[100:101], v[100:101], v[106:107]
	s_nop 0
	v_add_f32_e32 v0, v100, v101
	v_add_f32_e32 v100, 0, v0
	v_mov_b32_e32 v101, v50
	v_pk_add_f32 v[96:97], v[100:101], v[98:99]
	s_nop 0
	v_pk_add_f32 v[94:95], v[96:97], v[94:95]
	s_nop 0
	v_add_f32_e32 v0, v94, v95
	v_mov_b32_e32 v94, v0
	s_nop 1
	v_permlane32_swap_b32_e32 v0, v94
	v_add_f32_e32 v0, v0, v94
	v_mov_b32_e32 v94, v0
	s_nop 1
	v_permlane16_swap_b32_e32 v0, v94
	v_add_f32_e32 v0, v0, v94
	s_nop 1
	v_add_f32_dpp v0, v0, v0 row_ror:8 row_mask:0xf bank_mask:0xf
	s_nop 1
	v_mov_b32_dpp v94, v0 row_shl:4 row_mask:0xf bank_mask:0x5
	v_mov_b32_dpp v94, v0 row_shr:4 row_mask:0xf bank_mask:0xa
	v_add_f32_e32 v0, v0, v94
	s_nop 1
	v_add_f32_dpp v0, v0, v0 quad_perm:[2,3,0,1] row_mask:0xf bank_mask:0xf
	s_nop 1
	v_add_f32_dpp v0, v0, v0 quad_perm:[1,0,3,2] row_mask:0xf bank_mask:0xf
	v_mul_f32_e32 v0, 0x3a800000, v0
	v_pk_add_f32 v[96:97], v[90:91], v[0:1] op_sel_hi:[1,0] neg_lo:[0,1] neg_hi:[0,1]
	v_pk_add_f32 v[98:99], v[92:93], v[0:1] op_sel_hi:[1,0] neg_lo:[0,1] neg_hi:[0,1]
	v_mov_b32_e32 v92, v97
	v_mov_b32_e32 v93, v99
	v_mov_b32_e32 v90, v96
	v_mov_b32_e32 v91, v98
	v_pk_mul_f32 v[92:93], v[92:93], v[92:93]
	s_nop 0
	v_pk_fma_f32 v[90:91], v[90:91], v[90:91], v[92:93]
	v_pk_add_f32 v[92:93], v[58:59], v[0:1] op_sel_hi:[1,0] neg_lo:[0,1] neg_hi:[0,1]
	v_pk_add_f32 v[94:95], v[90:91], v[90:91] op_sel_hi:[0,1]
	v_pk_add_f32 v[90:91], v[60:61], v[0:1] op_sel_hi:[1,0] neg_lo:[0,1] neg_hi:[0,1]
	v_mov_b32_e32 v60, v93
	v_mov_b32_e32 v61, v91
	v_mov_b32_e32 v58, v92
	v_mov_b32_e32 v59, v90
	v_pk_mul_f32 v[60:61], v[60:61], v[60:61]
	s_nop 0
	v_pk_fma_f32 v[58:59], v[58:59], v[58:59], v[60:61]
	v_pk_add_f32 v[60:61], v[54:55], v[0:1] op_sel_hi:[1,0] neg_lo:[0,1] neg_hi:[0,1]
	v_pk_add_f32 v[100:101], v[58:59], v[58:59] op_sel_hi:[0,1]
	v_pk_add_f32 v[58:59], v[56:57], v[0:1] op_sel_hi:[1,0] neg_lo:[0,1] neg_hi:[0,1]
	v_mul_f32_e32 v54, v60, v60
	v_pk_fma_f32 v[106:107], v[60:61], v[60:61], v[54:55] op_sel_hi:[1,1,0]
	v_mul_f32_e32 v54, v58, v58
	v_pk_fma_f32 v[108:109], v[58:59], v[58:59], v[54:55] op_sel_hi:[1,1,0]
	v_pk_add_f32 v[56:57], v[50:51], v[0:1] op_sel_hi:[1,0] neg_lo:[0,1] neg_hi:[0,1]
	v_pk_add_f32 v[54:55], v[52:53], v[0:1] op_sel_hi:[1,0] neg_lo:[0,1] neg_hi:[0,1]
	v_pk_mul_f32 v[50:51], v[56:57], v[56:57]
	v_pk_mul_f32 v[52:53], v[54:55], v[54:55]
	v_mov_b32_e32 v106, v50
	v_mov_b32_e32 v108, v51
	v_mov_b32_e32 v94, v52
	v_mov_b32_e32 v100, v53
	v_pk_add_f32 v[50:51], v[106:107], v[108:109]
	v_pk_add_f32 v[52:53], v[94:95], v[100:101]
	s_nop 0
	v_pk_add_f32 v[50:51], v[50:51], v[52:53]
	s_nop 0
	v_add_f32_e32 v0, v50, v51
	v_mov_b32_e32 v50, v0
	s_nop 1
	v_permlane32_swap_b32_e32 v0, v50
	v_add_f32_e32 v0, v0, v50
	v_mov_b32_e32 v50, v0
	s_nop 1
	v_permlane16_swap_b32_e32 v0, v50
	v_add_f32_e32 v0, v0, v50
	s_nop 1
	v_add_f32_dpp v0, v0, v0 row_ror:8 row_mask:0xf bank_mask:0xf
	s_nop 1
	v_mov_b32_dpp v50, v0 row_shl:4 row_mask:0xf bank_mask:0x5
	v_mov_b32_dpp v50, v0 row_shr:4 row_mask:0xf bank_mask:0xa
	v_add_f32_e32 v0, v0, v50
	s_nop 1
	v_add_f32_dpp v0, v0, v0 quad_perm:[2,3,0,1] row_mask:0xf bank_mask:0xf
	s_nop 1
	v_add_f32_dpp v0, v0, v0 quad_perm:[1,0,3,2] row_mask:0xf bank_mask:0xf
	v_mov_b32_e32 v50, 0x3727c5ac
	v_fmamk_f32 v0, v0, 0x3a800000, v50
	v_cmp_gt_f32_e32 vcc, s37, v0
	v_mul_f32_e32 v50, 0x4b800000, v0
	s_nop 0
	v_cndmask_b32_e32 v0, v0, v50, vcc
	v_rsq_f32_e32 v0, v0
	s_nop 0
	v_mul_f32_e32 v50, 0x45800000, v0
	v_cndmask_b32_e32 v94, v0, v50, vcc
	v_pk_mul_f32 v[50:51], v[96:97], v[94:95] op_sel_hi:[1,0]
	v_pk_mul_f32 v[52:53], v[98:99], v[94:95] op_sel_hi:[1,0]
	v_pk_fma_f32 v[50:51], v[2:3], v[50:51], v[10:11]
	v_pk_fma_f32 v[52:53], v[4:5], v[52:53], v[12:13]
	v_lshl_add_u64 v[96:97], v[82:83], 0, v[78:79]
	s_and_saveexec_b64 s[42:43], s[52:53]
	s_cbranch_execz .LBB0_34
	global_store_dwordx4 v[96:97], v[50:53], off

; DI void phase_ln(const P& p, int l) {
;     ...
;     for (int h = 0; h < 2; ++h) {
;       if (h && !two) break;
;       const int rr = h ? rowb : row;
;       float s = 0.f;
; #pragma unroll
;       for (int i = 0; i < 4; ++i) s += (v[h][i].x + v[h][i].y) + (v[h][i].z + v[h][i].w);
; #pragma unroll
;       for (int o = 32; o >= 1; o >>= 1) s += __shfl_xor(s, o);
;       const float mean = s * (1.f / 1024.f);
;       float q = 0.f;
; #pragma unroll
;       for (int i = 0; i < 4; ++i) {
;         v[h][i].x -= mean; v[h][i].y -= mean; v[h][i].z -= mean; v[h][i].w -= mean;
;         q += (v[h][i].x * v[h][i].x + v[h][i].y * v[h][i].y) + (v[h][i].z * v[h][i].z + v[h][i].w * v[h][i].w);
;       }
; #pragma unroll
;       for (int o = 32; o >= 1; o >>= 1) q += __shfl_xor(q, o);
;       const float rstd = rsqrtf(q * (1.f / 1024.f) + 1e-5f);
;       const int mr = rr < MLAT ? (rr >> 11) : 16;
;       const float* md = p.mod + (size_t)(1 * 17 + mr) * 3072;
; #pragma unroll
;       for (int i = 0; i < 4; ++i) {
;         const int col = i * 256 + lane * 4;
;         float4 y;
;         y.x = v[h][i].x * rstd * g4[i].x + b4[i].x;
;         y.y = v[h][i].y * rstd * g4[i].y + b4[i].y;
;         y.z = v[h][i].z * rstd * g4[i].z + b4[i].z;
;         y.w = v[h][i].w * rstd * g4[i].w + b4[i].w;
;         if (l == 1 || rr < MLAT) *(float4*)(p.out + (size_t)rr * 1024 + col) = y;
.LBB0_49:
	v_mov_b32_e32 v50, v34
	v_mov_b32_e32 v51, v36
	v_mov_b32_e32 v52, v35
	v_mov_b32_e32 v53, v37
	v_pk_add_f32 v[50:51], v[50:51], v[52:53]
	v_mov_b32_e32 v52, v46
	v_mov_b32_e32 v53, v48
	v_mov_b32_e32 v54, v47
	v_mov_b32_e32 v55, v49
	v_pk_add_f32 v[52:53], v[52:53], v[54:55]
	v_mov_b32_e32 v54, v43
	v_mov_b32_e32 v56, v45
	v_add_f32_e32 v50, v50, v51
	v_pk_add_f32 v[52:53], v[52:53], v[52:53] op_sel:[0,1] op_sel_hi:[1,0]
	v_pk_add_f32 v[54:55], v[42:43], v[54:55]
	v_pk_add_f32 v[56:57], v[44:45], v[56:57]
	v_add_f32_e32 v50, 0, v50
	v_mov_b32_e32 v51, v38
	v_mov_b32_e32 v53, v39
	v_mov_b32_e32 v55, v40
	v_mov_b32_e32 v57, v41
	v_pk_add_f32 v[50:51], v[50:51], v[52:53]
	v_pk_add_f32 v[52:53], v[54:55], v[56:57]
	s_movk_i32 s2, 0x7fff
	v_pk_add_f32 v[50:51], v[50:51], v[52:53]
	v_cmp_gt_i32_e32 vcc, s2, v62
	v_add_f32_e32 v50, v50, v51
	s_or_b64 s[40:41], s[46:47], vcc
	v_mov_b32_e32 v51, v50
	s_nop 1
	v_permlane32_swap_b32_e32 v50, v51
	v_add_f32_e32 v50, v50, v51
	v_mov_b32_e32 v51, v50
	s_nop 1
	v_permlane16_swap_b32_e32 v50, v51
	v_add_f32_e32 v50, v50, v51
	s_nop 1
	v_add_f32_dpp v50, v50, v50 row_ror:8 row_mask:0xf bank_mask:0xf
	s_nop 1
	v_mov_b32_dpp v51, v50 row_shl:4 row_mask:0xf bank_mask:0x5
	v_mov_b32_dpp v51, v50 row_shr:4 row_mask:0xf bank_mask:0xa
	v_add_f32_e32 v50, v50, v51
	s_nop 1
	v_add_f32_dpp v50, v50, v50 quad_perm:[2,3,0,1] row_mask:0xf bank_mask:0xf
	s_nop 1
	v_add_f32_dpp v50, v50, v50 quad_perm:[1,0,3,2] row_mask:0xf bank_mask:0xf
	v_mul_f32_e32 v52, 0x3a800000, v50
	v_pk_add_f32 v[50:51], v[46:47], v[52:53] op_sel_hi:[1,0] neg_lo:[0,1] neg_hi:[0,1]
	v_pk_add_f32 v[48:49], v[48:49], v[52:53] op_sel_hi:[1,0] neg_lo:[0,1] neg_hi:[0,1]
	v_mov_b32_e32 v54, v51
	v_mov_b32_e32 v55, v49
	v_mov_b32_e32 v46, v50
	v_mov_b32_e32 v47, v48
	v_pk_mul_f32 v[54:55], v[54:55], v[54:55]
	v_pk_add_f32 v[44:45], v[44:45], v[52:53] op_sel_hi:[1,0] neg_lo:[0,1] neg_hi:[0,1]
	v_pk_fma_f32 v[46:47], v[46:47], v[46:47], v[54:55]
	v_pk_add_f32 v[36:37], v[36:37], v[52:53] op_sel_hi:[1,0] neg_lo:[0,1] neg_hi:[0,1]
	v_pk_add_f32 v[54:55], v[46:47], v[46:47] op_sel_hi:[0,1]
	v_pk_add_f32 v[46:47], v[42:43], v[52:53] op_sel_hi:[1,0] neg_lo:[0,1] neg_hi:[0,1]
	v_pk_add_f32 v[34:35], v[34:35], v[52:53] op_sel_hi:[1,0] neg_lo:[0,1] neg_hi:[0,1]
	v_mul_f32_e32 v42, v46, v46
	v_pk_fma_f32 v[56:57], v[46:47], v[46:47], v[42:43] op_sel_hi:[1,1,0]
	v_mul_f32_e32 v42, v44, v44
	v_mov_b32_e32 v90, v35
	v_mov_b32_e32 v91, v37
	v_pk_fma_f32 v[58:59], v[44:45], v[44:45], v[42:43] op_sel_hi:[1,1,0]
	v_pk_add_f32 v[42:43], v[38:39], v[52:53] op_sel_hi:[1,0] neg_lo:[0,1] neg_hi:[0,1]
	v_pk_add_f32 v[38:39], v[40:41], v[52:53] op_sel_hi:[1,0] neg_lo:[0,1] neg_hi:[0,1]
	v_mov_b32_e32 v52, v34
	v_mov_b32_e32 v53, v36
	v_pk_mul_f32 v[90:91], v[90:91], v[90:91]
	v_pk_mul_f32 v[40:41], v[42:43], v[42:43]
	v_pk_fma_f32 v[52:53], v[52:53], v[52:53], v[90:91]
	v_pk_mul_f32 v[60:61], v[38:39], v[38:39]
	v_pk_add_f32 v[52:53], v[52:53], v[52:53] op_sel_hi:[0,1]
	v_mov_b32_e32 v56, v40
	v_mov_b32_e32 v58, v41
	v_mov_b32_e32 v52, v60
	v_mov_b32_e32 v54, v61
	v_pk_add_f32 v[40:41], v[56:57], v[58:59]
	v_pk_add_f32 v[52:53], v[52:53], v[54:55]
	s_nop 0
	v_pk_add_f32 v[40:41], v[40:41], v[52:53]
	v_lshl_add_u64 v[52:53], v[74:75], 0, v[88:89]
	v_add_f32_e32 v40, v40, v41
	v_mov_b32_e32 v41, v40
	s_nop 1
	v_permlane32_swap_b32_e32 v40, v41
	v_add_f32_e32 v40, v40, v41
	v_mov_b32_e32 v41, v40
	s_nop 1
	v_permlane16_swap_b32_e32 v40, v41
	v_add_f32_e32 v40, v40, v41
	s_nop 1
	v_add_f32_dpp v40, v40, v40 row_ror:8 row_mask:0xf bank_mask:0xf
	s_nop 1
	v_mov_b32_dpp v41, v40 row_shl:4 row_mask:0xf bank_mask:0x5
	v_mov_b32_dpp v41, v40 row_shr:4 row_mask:0xf bank_mask:0xa
	v_add_f32_e32 v40, v40, v41
	s_nop 1
	v_add_f32_dpp v40, v40, v40 quad_perm:[2,3,0,1] row_mask:0xf bank_mask:0xf
	s_nop 1
	v_add_f32_dpp v40, v40, v40 quad_perm:[1,0,3,2] row_mask:0xf bank_mask:0xf
	v_mov_b32_e32 v41, 0x3727c5ac
	v_fmamk_f32 v40, v40, 0x3a800000, v41
	v_cmp_gt_f32_e32 vcc, s37, v40
	v_mul_f32_e32 v41, 0x4b800000, v40
	s_nop 0
	v_cndmask_b32_e32 v40, v40, v41, vcc
	v_rsq_f32_e32 v40, v40
	s_nop 0
	v_mul_f32_e32 v41, 0x45800000, v40
	v_cndmask_b32_e32 v40, v40, v41, vcc
	v_pk_mul_f32 v[34:35], v[34:35], v[40:41] op_sel_hi:[1,0]
	v_pk_mul_f32 v[36:37], v[36:37], v[40:41] op_sel_hi:[1,0]
	v_pk_fma_f32 v[34:35], v[2:3], v[34:35], v[10:11]
	v_pk_fma_f32 v[36:37], v[4:5], v[36:37], v[12:13]
	s_and_saveexec_b64 s[54:55], s[40:41]
	s_cbranch_execz .LBB0_51
	global_store_dwordx4 v[52:53], v[34:37], off
